# DN gates for chunk n+1 computed by wave 5 in step BC(n) (off the step-A critical path)
# baseline (speedup 1.0000x reference)
; DI float sigmoidf_(float x) { return __builtin_amdgcn_rcpf(1.f + __expf(-x)); }
; DI float softplusf_(float x) { return x > 20.f ? x : log1pf(expf(x)); }
; template <bool CONS>
; DI void dn_chain_role(const Params& p, unsigned char* smem, int dir, int b, int h) {
;     ...
; #pragma unroll
;             for (int it = 0; it < 4; ++it) {
;                 const int idx = tid - 256 + 256 * it, i = idx >> 4, c8 = idx & 15;
;                 *(u32x4*)(sQ + i * ST + c8 * 8) = pq[it]; *(u32x4*)(sK + i * ST + c8 * 8) = pk[it]; *(u32x4*)(sV + i * ST + c8 * 8) = pv[it];
;             }
;         }
;         if (!CONS && wave == 5) {
;             const float beta = sigmoidf_(pbr), g = -a_coef * softplusf_(par + dtb);
.LBB0_522:
	v_mov_b32_e32 v138, v131
	s_add_i32 s22, s52, 3
	s_bitcmp0_b32 s22, 0
	s_nop 0
	v_or_b32_e32 v5, s45, v138
	v_lshlrev_b32_e32 v1, 3, v138
	v_add_u32_e32 v0, 0xffffff00, v5
	v_and_b32_e32 v4, 0x78, v1
	s_cselect_b32 s8, s53, 0x1ca00
	v_lshl_add_u32 v6, v4, 1, 0
	v_ashrrev_i32_e32 v3, 4, v0
	s_add_i32 s78, s8, 0
	v_mad_u64_u32 v[0:1], s[8:9], v3, s54, v[6:7]
	v_ashrrev_i32_e32 v2, 4, v5
	s_waitcnt vmcnt(11)
	ds_write_b128 v0, v[16:19]
	s_waitcnt vmcnt(10)
	ds_write_b128 v0, v[20:23] offset:17408
	s_waitcnt vmcnt(9)
	ds_write_b128 v0, v[24:27] offset:34816
	v_mad_u64_u32 v[0:1], s[8:9], v2, s54, v[6:7]
	s_waitcnt vmcnt(8)
	ds_write_b128 v0, v[28:31]
	s_waitcnt vmcnt(7)
	ds_write_b128 v0, v[32:35] offset:17408
	s_waitcnt vmcnt(6)
	ds_write_b128 v0, v[36:39] offset:34816
	v_add_u32_e32 v0, 0x100, v5
	v_ashrrev_i32_e32 v1, 4, v0
	v_add_u32_e32 v0, 0x200, v5
	v_ashrrev_i32_e32 v0, 4, v0
	v_mad_u64_u32 v[8:9], s[8:9], v1, s54, v[6:7]
	v_mad_u64_u32 v[6:7], s[8:9], v0, s54, v[6:7]
	s_and_b64 vcc, exec, s[6:7]
	s_waitcnt vmcnt(5)
	ds_write_b128 v8, v[40:43]
	s_waitcnt vmcnt(4)
	ds_write_b128 v8, v[44:47] offset:17408
	s_waitcnt vmcnt(3)
	ds_write_b128 v8, v[48:51] offset:34816
	s_waitcnt vmcnt(2)
	ds_write_b128 v6, v[52:55]
	s_waitcnt vmcnt(1)
	ds_write_b128 v6, v[56:59] offset:17408
	s_waitcnt vmcnt(0)
	ds_write_b128 v6, v[60:63] offset:34816
	s_cbranch_vccnz .LBB0_526
	s_cmp_lg_u32 s22, 0
	s_cbranch_scc1 .LBB0_526
	v_add_f32_e32 v5, v130, v125
	v_cmp_nlt_f32_e32 vcc, s56, v5
	s_and_saveexec_b64 s[8:9], vcc
	s_cbranch_execz .LBB0_525
	v_mul_f32_e32 v6, 0x3fb8aa3b, v5
	v_rndne_f32_e32 v7, v6
	v_sub_f32_e32 v8, v6, v7
	v_fma_f32 v6, v5, s38, -v6
	v_fmac_f32_e32 v6, 0x32a5705f, v5
	v_add_f32_e32 v6, v8, v6
	v_cvt_i32_f32_e32 v7, v7
	v_exp_f32_e32 v6, v6
	v_cmp_ngt_f32_e32 vcc, s39, v5
	v_ldexp_f32 v6, v6, v7
	s_nop 0
	v_cndmask_b32_e32 v6, 0, v6, vcc
	v_cmp_nlt_f32_e32 vcc, s40, v5
	s_nop 1
	v_cndmask_b32_e32 v5, v133, v6, vcc
	v_add_f32_e32 v8, 1.0, v5
	v_add_f32_e32 v6, -1.0, v8
	v_sub_f32_e32 v7, v6, v8
	v_add_f32_e32 v7, 1.0, v7
	v_sub_f32_e32 v6, v5, v6
	v_add_f32_e32 v9, v6, v7
	v_frexp_mant_f32_e32 v10, v8
	v_cvt_f64_f32_e32 v[6:7], v8
	v_frexp_exp_i32_f64_e32 v6, v[6:7]
	v_cmp_gt_f32_e32 vcc, s57, v10
	s_nop 1
	v_subbrev_co_u32_e32 v14, vcc, 0, v6, vcc
	v_sub_u32_e32 v6, 0, v14
	v_ldexp_f32 v7, v8, v6
	v_add_f32_e32 v8, -1.0, v7
	v_add_f32_e32 v10, 1.0, v7
	v_ldexp_f32 v6, v9, v6
	v_add_f32_e32 v9, 1.0, v8
	v_add_f32_e32 v11, -1.0, v10
	v_sub_f32_e32 v9, v7, v9
	v_sub_f32_e32 v7, v7, v11
	v_add_f32_e32 v9, v6, v9
	v_add_f32_e32 v6, v6, v7
	v_add_f32_e32 v15, v10, v6
	v_rcp_f32_e32 v65, v15
	v_sub_f32_e32 v7, v10, v15
	v_add_f32_e32 v64, v6, v7
	v_add_f32_e32 v7, v8, v9
	v_mul_f32_e32 v67, v7, v65
	v_sub_f32_e32 v6, v8, v7
	v_mul_f32_e32 v8, v15, v67
	v_fma_f32 v10, v67, v15, -v8
	v_fmac_f32_e32 v10, v67, v64
	v_add_f32_e32 v66, v9, v6
	v_add_f32_e32 v6, v8, v10
	v_sub_f32_e32 v9, v7, v6
	v_pk_add_f32 v[12:13], v[6:7], v[8:9] neg_lo:[0,1] neg_hi:[0,1]
	v_mov_b32_e32 v11, v6
	v_pk_add_f32 v[6:7], v[12:13], v[10:11] neg_lo:[0,1] neg_hi:[0,1]
	v_cmp_neq_f32_e32 vcc, s41, v5
	v_add_f32_e32 v7, v66, v7
	v_add_f32_e32 v6, v6, v7
	v_add_f32_e32 v7, v9, v6
	v_mul_f32_e32 v66, v65, v7
	v_mul_f32_e32 v8, v15, v66
	v_fma_f32 v10, v66, v15, -v8
	v_fmac_f32_e32 v10, v66, v64
	v_sub_f32_e32 v9, v9, v7
	v_add_f32_e32 v15, v6, v9
	v_add_f32_e32 v6, v8, v10
	v_sub_f32_e32 v9, v7, v6
	v_pk_add_f32 v[12:13], v[6:7], v[8:9] neg_lo:[0,1] neg_hi:[0,1]
	v_mov_b32_e32 v11, v6
	v_pk_add_f32 v[6:7], v[12:13], v[10:11] neg_lo:[0,1] neg_hi:[0,1]
	s_nop 0
	v_add_f32_e32 v7, v15, v7
	v_add_f32_e32 v6, v6, v7
	v_add_f32_e32 v7, v67, v66
	v_add_f32_e32 v6, v9, v6
	v_sub_f32_e32 v8, v7, v67
	v_mul_f32_e32 v6, v65, v6
	v_sub_f32_e32 v8, v66, v8
	v_add_f32_e32 v8, v8, v6
	v_add_f32_e32 v10, v7, v8
	v_mul_f32_e32 v11, v10, v10
	v_fmamk_f32 v6, v11, 0x3e9b6dac, v135
	v_fmaak_f32 v129, v11, v6, 0x3f2aaada
	v_cvt_f32_i32_e32 v6, v14
	v_sub_f32_e32 v7, v10, v7
	v_sub_f32_e32 v7, v8, v7
	v_ldexp_f32 v12, v7, 1
	v_mul_f32_e32 v7, v10, v11
	v_ldexp_f32 v9, v10, 1
	v_pk_mul_f32 v[10:11], v[6:7], v[128:129]
	s_nop 0
	v_fma_f32 v8, v6, s60, -v10
	v_fmac_f32_e32 v8, 0xb102e308, v6
	v_pk_add_f32 v[6:7], v[10:11], v[8:9]
	s_nop 0
	v_sub_f32_e32 v9, v7, v9
	v_sub_f32_e32 v9, v11, v9
	v_add_f32_e32 v13, v12, v9
	v_mov_b32_e32 v12, v10
	v_pk_add_f32 v[10:11], v[6:7], v[10:11] neg_lo:[0,1] neg_hi:[0,1]
	v_pk_add_f32 v[14:15], v[6:7], v[12:13]
	v_mov_b32_e32 v9, v6
	v_mov_b32_e32 v11, v15
	v_pk_add_f32 v[64:65], v[8:9], v[10:11] neg_lo:[0,1] neg_hi:[0,1]
	v_pk_add_f32 v[8:9], v[8:9], v[10:11]
	v_mov_b32_e32 v12, v13
	v_pk_add_f32 v[10:11], v[8:9], v[6:7] op_sel:[1,0] op_sel_hi:[0,1] neg_lo:[0,1] neg_hi:[0,1]
	v_pk_add_f32 v[66:67], v[14:15], v[10:11] op_sel_hi:[1,0] neg_lo:[0,1] neg_hi:[0,1]
	v_mov_b32_e32 v14, v15
	v_mov_b32_e32 v15, v9
	v_pk_mov_b32 v[10:11], v[6:7], v[10:11] op_sel:[1,0]
	v_mov_b32_e32 v13, v6
	v_pk_add_f32 v[10:11], v[14:15], v[10:11] neg_lo:[0,1] neg_hi:[0,1]
	v_mov_b32_e32 v66, v64
	v_pk_add_f32 v[6:7], v[12:13], v[10:11] neg_lo:[0,1] neg_hi:[0,1]
	v_mov_b32_e32 v65, v9
	v_pk_add_f32 v[10:11], v[66:67], v[6:7]
	s_nop 0
	v_pk_add_f32 v[12:13], v[10:11], v[10:11] op_sel:[0,1] op_sel_hi:[1,0]
	s_nop 0
	v_pk_add_f32 v[8:9], v[8:9], v[12:13] op_sel:[1,0] op_sel_hi:[0,1]
	v_mov_b32_e32 v11, v8
	v_pk_add_f32 v[14:15], v[10:11], v[64:65] neg_lo:[0,1] neg_hi:[0,1]
	v_mov_b32_e32 v7, v12
	v_sub_f32_e32 v9, v10, v14
	v_pk_add_f32 v[6:7], v[6:7], v[14:15] neg_lo:[0,1] neg_hi:[0,1]
	v_sub_f32_e32 v9, v64, v9
	v_add_f32_e32 v6, v6, v9
	v_add_f32_e32 v6, v6, v7
	v_add_f32_e32 v6, v8, v6
	v_cndmask_b32_e32 v6, v133, v6, vcc
	v_cmp_lt_f32_e64 vcc, |v5|, s61
	s_nop 1
	v_cndmask_b32_e32 v5, v6, v5, vcc

; DI float sigmoidf_(float x) { return __builtin_amdgcn_rcpf(1.f + __expf(-x)); }
; DI float softplusf_(float x) { return x > 20.f ? x : log1pf(expf(x)); }
; template <bool CONS>
; DI void dn_chain_role(const Params& p, unsigned char* smem, int dir, int b, int h) {
;     ...
;         if (!CONS && wave == 5) {
;             const float beta = sigmoidf_(pbr), g = -a_coef * softplusf_(par + dtb);
;             float G = g;
; #pragma unroll
;             for (int o = 1; o < 64; o <<= 1) { const float t = __shfl_up(G, o); if (lane >= o) G += t; }
;             const float Gl = __shfl(G, 63), eG = expf(G);
;             sG[lane] = G * 1.4426950408889634f; sBeta[lane] = beta; sEG[lane] = eG; sDL[lane] = expf(Gl - G); sRow[lane] = prow;
.LBB0_545:
	s_andn2_b64 vcc, exec, s[8:9]
	s_cbranch_vccz .Lg5_solve
	s_cmp_eq_u32 s24, 5
	s_cbranch_scc0 .LBB0_521
	s_cmp_eq_u32 s52, 64
	s_cbranch_scc1 .LBB0_521
	s_bitcmp0_b32 s52, 0
	s_cselect_b32 s86, s53, 0x1ca00
	s_waitcnt vmcnt(0)
	v_add_f32_e32 v5, v130, v125
	v_cmp_nlt_f32_e32 vcc, s56, v5
	s_and_saveexec_b64 s[8:9], vcc
	s_cbranch_execz .Lg5_525
	v_mul_f32_e32 v6, 0x3fb8aa3b, v5
	v_rndne_f32_e32 v7, v6
	v_sub_f32_e32 v8, v6, v7
	v_fma_f32 v6, v5, s38, -v6
	v_fmac_f32_e32 v6, 0x32a5705f, v5
	v_add_f32_e32 v6, v8, v6
	v_cvt_i32_f32_e32 v7, v7
	v_exp_f32_e32 v6, v6
	v_cmp_ngt_f32_e32 vcc, s39, v5
	v_ldexp_f32 v6, v6, v7
	s_nop 0
	v_cndmask_b32_e32 v6, 0, v6, vcc
	v_cmp_nlt_f32_e32 vcc, s40, v5
	s_nop 1
	v_cndmask_b32_e32 v5, v133, v6, vcc
	v_add_f32_e32 v8, 1.0, v5
	v_add_f32_e32 v6, -1.0, v8
	v_sub_f32_e32 v7, v6, v8
	v_add_f32_e32 v7, 1.0, v7
	v_sub_f32_e32 v6, v5, v6
	v_add_f32_e32 v9, v6, v7
	v_frexp_mant_f32_e32 v10, v8
	v_cvt_f64_f32_e32 v[6:7], v8
	v_frexp_exp_i32_f64_e32 v6, v[6:7]
	v_cmp_gt_f32_e32 vcc, s57, v10
	s_nop 1
	v_subbrev_co_u32_e32 v14, vcc, 0, v6, vcc
	v_sub_u32_e32 v6, 0, v14
	v_ldexp_f32 v7, v8, v6
	v_add_f32_e32 v8, -1.0, v7
	v_add_f32_e32 v10, 1.0, v7
	v_ldexp_f32 v6, v9, v6
	v_add_f32_e32 v9, 1.0, v8
	v_add_f32_e32 v11, -1.0, v10
	v_sub_f32_e32 v9, v7, v9
	v_sub_f32_e32 v7, v7, v11
	v_add_f32_e32 v9, v6, v9
	v_add_f32_e32 v6, v6, v7
	v_add_f32_e32 v15, v10, v6
	v_rcp_f32_e32 v65, v15
	v_sub_f32_e32 v7, v10, v15
	v_add_f32_e32 v64, v6, v7
	v_add_f32_e32 v7, v8, v9
	v_mul_f32_e32 v67, v7, v65
	v_sub_f32_e32 v6, v8, v7
	v_mul_f32_e32 v8, v15, v67
	v_fma_f32 v10, v67, v15, -v8
	v_fmac_f32_e32 v10, v67, v64
	v_add_f32_e32 v66, v9, v6
	v_add_f32_e32 v6, v8, v10
	v_sub_f32_e32 v9, v7, v6
	v_pk_add_f32 v[12:13], v[6:7], v[8:9] neg_lo:[0,1] neg_hi:[0,1]
	v_mov_b32_e32 v11, v6
	v_pk_add_f32 v[6:7], v[12:13], v[10:11] neg_lo:[0,1] neg_hi:[0,1]
	v_cmp_neq_f32_e32 vcc, s41, v5
	v_add_f32_e32 v7, v66, v7
	v_add_f32_e32 v6, v6, v7
	v_add_f32_e32 v7, v9, v6
	v_mul_f32_e32 v66, v65, v7
	v_mul_f32_e32 v8, v15, v66
	v_fma_f32 v10, v66, v15, -v8
	v_fmac_f32_e32 v10, v66, v64
	v_sub_f32_e32 v9, v9, v7
	v_add_f32_e32 v15, v6, v9
	v_add_f32_e32 v6, v8, v10
	v_sub_f32_e32 v9, v7, v6
	v_pk_add_f32 v[12:13], v[6:7], v[8:9] neg_lo:[0,1] neg_hi:[0,1]
	v_mov_b32_e32 v11, v6
	v_pk_add_f32 v[6:7], v[12:13], v[10:11] neg_lo:[0,1] neg_hi:[0,1]
	s_nop 0
	v_add_f32_e32 v7, v15, v7
	v_add_f32_e32 v6, v6, v7
	v_add_f32_e32 v7, v67, v66
	v_add_f32_e32 v6, v9, v6
	v_sub_f32_e32 v8, v7, v67
	v_mul_f32_e32 v6, v65, v6
	v_sub_f32_e32 v8, v66, v8
	v_add_f32_e32 v8, v8, v6
	v_add_f32_e32 v10, v7, v8
	v_mul_f32_e32 v11, v10, v10
	v_fmamk_f32 v6, v11, 0x3e9b6dac, v135
	v_fmaak_f32 v129, v11, v6, 0x3f2aaada
	v_cvt_f32_i32_e32 v6, v14
	v_sub_f32_e32 v7, v10, v7
	v_sub_f32_e32 v7, v8, v7
	v_ldexp_f32 v12, v7, 1
	v_mul_f32_e32 v7, v10, v11
	v_ldexp_f32 v9, v10, 1
	v_pk_mul_f32 v[10:11], v[6:7], v[128:129]
	s_nop 0
	v_fma_f32 v8, v6, s60, -v10
	v_fmac_f32_e32 v8, 0xb102e308, v6
	v_pk_add_f32 v[6:7], v[10:11], v[8:9]
	s_nop 0
	v_sub_f32_e32 v9, v7, v9
	v_sub_f32_e32 v9, v11, v9
	v_add_f32_e32 v13, v12, v9
	v_mov_b32_e32 v12, v10
	v_pk_add_f32 v[10:11], v[6:7], v[10:11] neg_lo:[0,1] neg_hi:[0,1]
	v_pk_add_f32 v[14:15], v[6:7], v[12:13]
	v_mov_b32_e32 v9, v6
	v_mov_b32_e32 v11, v15
	v_pk_add_f32 v[64:65], v[8:9], v[10:11] neg_lo:[0,1] neg_hi:[0,1]
	v_pk_add_f32 v[8:9], v[8:9], v[10:11]
	v_mov_b32_e32 v12, v13
	v_pk_add_f32 v[10:11], v[8:9], v[6:7] op_sel:[1,0] op_sel_hi:[0,1] neg_lo:[0,1] neg_hi:[0,1]
	v_pk_add_f32 v[66:67], v[14:15], v[10:11] op_sel_hi:[1,0] neg_lo:[0,1] neg_hi:[0,1]
	v_mov_b32_e32 v14, v15
	v_mov_b32_e32 v15, v9
	v_pk_mov_b32 v[10:11], v[6:7], v[10:11] op_sel:[1,0]
	v_mov_b32_e32 v13, v6
	v_pk_add_f32 v[10:11], v[14:15], v[10:11] neg_lo:[0,1] neg_hi:[0,1]
	v_mov_b32_e32 v66, v64
	v_pk_add_f32 v[6:7], v[12:13], v[10:11] neg_lo:[0,1] neg_hi:[0,1]
	v_mov_b32_e32 v65, v9
	v_pk_add_f32 v[10:11], v[66:67], v[6:7]
	s_nop 0
	v_pk_add_f32 v[12:13], v[10:11], v[10:11] op_sel:[0,1] op_sel_hi:[1,0]
	s_nop 0
	v_pk_add_f32 v[8:9], v[8:9], v[12:13] op_sel:[1,0] op_sel_hi:[0,1]
	v_mov_b32_e32 v11, v8
	v_pk_add_f32 v[14:15], v[10:11], v[64:65] neg_lo:[0,1] neg_hi:[0,1]
	v_mov_b32_e32 v7, v12
	v_sub_f32_e32 v9, v10, v14
	v_pk_add_f32 v[6:7], v[6:7], v[14:15] neg_lo:[0,1] neg_hi:[0,1]
	v_sub_f32_e32 v9, v64, v9
	v_add_f32_e32 v6, v6, v9
	v_add_f32_e32 v6, v6, v7
	v_add_f32_e32 v6, v8, v6
	v_cndmask_b32_e32 v6, v133, v6, vcc
	v_cmp_lt_f32_e64 vcc, |v5|, s61
	s_nop 1
	v_cndmask_b32_e32 v5, v6, v5, vcc
.Lg5_525:
	s_or_b64 exec, exec, s[8:9]
	v_mul_f32_e64 v5, v5, -v134
	v_mul_f32_e32 v7, 0xbfb8aa3b, v132
	v_exp_f32_e32 v7, v7
	v_add_f32_dpp v5, v5, v5 row_shr:1 row_mask:0xf bank_mask:0xf
	v_add_f32_e32 v7, 1.0, v7
	s_nop 0
	v_add_f32_dpp v5, v5, v5 row_shr:2 row_mask:0xf bank_mask:0xf
	v_rcp_f32_e32 v7, v7
	s_nop 0
	v_add_f32_dpp v5, v5, v5 row_shr:4 row_mask:0xf bank_mask:0xf
	s_nop 1
	v_add_f32_dpp v5, v5, v5 row_shr:8 row_mask:0xf bank_mask:0xf
	s_nop 1
	v_add_f32_dpp v5, v5, v5 row_bcast:15 row_mask:0xa bank_mask:0xf
	s_nop 1
	v_add_f32_dpp v5, v5, v5 row_bcast:31 row_mask:0xc bank_mask:0xf
	v_mul_f32_e32 v6, 0x3fb8aa3b, v5
	v_fma_f32 v8, v5, s38, -v6
	v_rndne_f32_e32 v9, v6
	v_fmac_f32_e32 v8, 0x32a5705f, v5
	v_sub_f32_e32 v10, v6, v9
	v_add_f32_e32 v8, v10, v8
	ds_bpermute_b32 v10, v137, v5
	v_exp_f32_e32 v8, v8
	v_cvt_i32_f32_e32 v9, v9
	v_cmp_ngt_f32_e32 vcc, s39, v5
	v_ldexp_f32 v8, v8, v9
	s_waitcnt lgkmcnt(0)
	v_sub_f32_e32 v9, v10, v5
	v_mul_f32_e32 v10, 0x3fb8aa3b, v9
	v_fma_f32 v11, v9, s38, -v10
	v_rndne_f32_e32 v12, v10
	v_fmac_f32_e32 v11, 0x32a5705f, v9
	v_sub_f32_e32 v10, v10, v12
	v_add_f32_e32 v10, v10, v11
	v_exp_f32_e32 v10, v10
	v_cvt_i32_f32_e32 v11, v12
	v_cndmask_b32_e32 v8, 0, v8, vcc
	v_cmp_nlt_f32_e32 vcc, s40, v5
	s_nop 1
	v_cndmask_b32_e32 v5, v133, v8, vcc
	v_lshl_add_u32 v8, v131, 2, s86
	ds_write2st64_b32 v8, v6, v7 offset1:1
	v_ldexp_f32 v6, v10, v11
	v_cmp_ngt_f32_e32 vcc, s39, v9
	s_nop 1
	v_cndmask_b32_e32 v6, 0, v6, vcc
	v_cmp_nlt_f32_e32 vcc, s40, v9
	s_nop 1
	v_cndmask_b32_e32 v6, v133, v6, vcc
	ds_write2st64_b32 v8, v5, v6 offset0:2 offset1:3
	ds_write_b32 v8, v124 offset:1280
	s_branch .LBB0_521
; DI bf16_t f2bf(float a) { return (bf16_t)(pk2(a, 0.f) & 0xffffu); }
; #define MFMA32(a, b, c) __builtin_amdgcn_mfma_f32_32x32x16_bf16((a), (b), (c), 0, 0, 0)
; template <bool CONS>
; DI void dn_chain_role(const Params& p, unsigned char* smem, int dir, int b, int h) {
;     ...
;             __builtin_amdgcn_s_setprio(3);
;             const int blk = wave == 4 ? 0 : 1;
;             bf16_t* sM1b = (bf16_t*)(smem + DM1 + 2560 * blk); bf16_t* sM2Tb = (bf16_t*)(smem + DM2T + 2560 * blk); bf16_t* sM3b = (bf16_t*)(smem + DM3 + 2560 * blk);
;             bf16_t* Tb = blk ? sT11 : sT00;
;             {
;                 f32x16 acc; for (int i = 0; i < 16; ++i) acc[i] = 0.f;
; #pragma unroll
;                 for (int s = 0; s < 8; ++s) { const bf16x8 a = load_nat(sK, ST, 32 * blk + r, 16 * s + 8 * hh); acc = MFMA32(a, a, acc); }
;                 const float Gj = sG[32 * blk + r];
;                 const int m1col = r < 16 ? r : 32 + (r & 7);
; #pragma unroll
;                 for (int g4 = 0; g4 < 4; ++g4) { const int il0 = 8 * g4 + 4 * hh; const f32x4 gi = *(const f32x4*)(sG + 32 * blk + il0), bi = *(const f32x4*)(sBeta + 32 * blk + il0);
; #pragma unroll
;                     for (int t = 0; t < 4; ++t) { const int il = il0 + t; const float v = il > r ? acc[4 * g4 + t] * bi[t] * __builtin_amdgcn_exp2f(gi[t] - Gj) : 0.f;
;                         sAd[(blk * 32 + il) * 36 + r] = v;
;                         if (g4 >= 2) sM1b[(il - 16) * 40 + m1col] = f2bf(v); } }
.Lg5_solve:
	s_setprio 3
	v_or_b32_e32 v0, s14, v126
	v_mul_u32_u24_e32 v0, 0x110, v0
	v_add3_u32 v65, 0, v0, v139
	ds_read_b128 v[0:3], v65 offset:17408
	ds_read_b128 v[66:69], v65 offset:17440
	s_lshl_b32 s8, s14, 2
	v_lshlrev_b32_e32 v74, 2, v126
	v_add_u32_e32 v75, s14, v129
	s_waitcnt lgkmcnt(1)
	v_mfma_f32_32x32x16_bf16 v[0:15], v[0:3], v[0:3], 0
	v_or_b32_e32 v140, 1, v129
	v_or_b32_e32 v83, 2, v129
	v_or_b32_e32 v92, 3, v129
	s_add_i32 s78, s78, s8
	v_add_u32_e32 v82, s74, v74
	v_add_u32_e32 v76, s14, v140
	v_add_u32_e32 v77, s14, v83
	s_waitcnt lgkmcnt(0)
	v_mfma_f32_32x32x16_bf16 v[0:15], v[66:69], v[66:69], v[0:15]
	ds_read_b128 v[66:69], v65 offset:17472
	ds_read_b128 v[70:73], v65 offset:17504
	v_add_u32_e32 v78, s14, v92
	v_add_u32_e32 v74, s78, v74
	v_mad_u64_u32 v[84:85], s[8:9], v75, s67, v[82:83]
	v_add_u32_e32 v96, s78, v139
	v_mad_u64_u32 v[86:87], s[8:9], v76, s67, v[82:83]
	s_waitcnt lgkmcnt(1)
	v_mfma_f32_32x32x16_bf16 v[0:15], v[66:69], v[66:69], v[0:15]
	ds_read_b128 v[66:69], v65 offset:17536
	v_mad_u64_u32 v[88:89], s[8:9], v77, s67, v[82:83]
	v_mad_u64_u32 v[90:91], s[8:9], v78, s67, v[82:83]
	v_cmp_gt_i32_e32 vcc, v129, v126
	v_add_u32_e32 v93, 8, v129
	s_waitcnt lgkmcnt(1)
	v_mfma_f32_32x32x16_bf16 v[0:15], v[70:73], v[70:73], v[0:15]
	ds_read_b128 v[70:73], v65 offset:17568
	v_add_u32_e32 v94, s14, v93
	v_add_u32_e32 v95, s51, v93
	v_mul_lo_u32 v141, v64, s76
	v_bfe_u32 v178, v138, 4, 1
	s_waitcnt lgkmcnt(1)
	v_mfma_f32_32x32x16_bf16 v[0:15], v[66:69], v[66:69], v[0:15]
	ds_read_b128 v[66:69], v65 offset:17600
	s_waitcnt lgkmcnt(1)
	v_mfma_f32_32x32x16_bf16 v[0:15], v[70:73], v[70:73], v[0:15]
	ds_read_b32 v85, v74
	ds_read_b128 v[70:73], v96
	ds_read_b128 v[74:77], v65 offset:17632
	ds_read_b128 v[78:81], v96 offset:256
	s_waitcnt lgkmcnt(2)
	v_sub_f32_e32 v65, v70, v85
	v_exp_f32_e32 v65, v65
	v_mfma_f32_32x32x16_bf16 v[0:15], v[66:69], v[66:69], v[0:15]
	v_sub_f32_e32 v66, v71, v85
	v_sub_f32_e32 v67, v72, v85
	v_exp_f32_e32 v66, v66
	v_sub_f32_e32 v68, v73, v85
	v_exp_f32_e32 v67, v67
	v_exp_f32_e32 v68, v68
	v_mad_u64_u32 v[70:71], s[8:9], v94, s67, v[82:83]
	s_waitcnt lgkmcnt(1)
	v_mfma_f32_32x32x16_bf16 v[0:15], v[74:77], v[74:77], v[0:15]
	v_mad_u64_u32 v[72:73], s[8:9], v95, s67, v[82:83]
	s_waitcnt lgkmcnt(0)
	s_nop 9
	v_mul_f32_e32 v0, v0, v78
	v_mul_f32_e32 v1, v1, v79
	v_mul_f32_e32 v0, v0, v65
	v_mul_f32_e32 v2, v2, v80
	v_mul_f32_e32 v1, v1, v66
	v_cndmask_b32_e32 v0, 0, v0, vcc
	v_cmp_ge_i32_e32 vcc, v129, v126
	v_mul_f32_e32 v3, v3, v81
	v_mul_f32_e32 v2, v2, v67
	v_cndmask_b32_e32 v1, 0, v1, vcc
	v_cmp_gt_i32_e32 vcc, v83, v126
	v_mul_f32_e32 v3, v3, v68
	v_and_or_b32 v65, v138, 7, 32
	v_cndmask_b32_e32 v2, 0, v2, vcc
	v_cmp_gt_i32_e32 vcc, v92, v126
	s_nop 1
	v_cndmask_b32_e32 v3, 0, v3, vcc
	ds_write_b32 v84, v0
	ds_write_b32 v86, v1
	ds_write_b32 v88, v2
	ds_write_b32 v90, v3
	ds_read_b128 v[0:3], v96 offset:32
	ds_read_b128 v[66:69], v96 offset:288
	v_cmp_gt_i32_e32 vcc, v93, v126
	s_waitcnt lgkmcnt(1)
	v_sub_f32_e32 v0, v0, v85
	v_exp_f32_e32 v0, v0
	v_sub_f32_e32 v1, v1, v85
	s_waitcnt lgkmcnt(0)
	v_mul_f32_e32 v4, v4, v66
	v_exp_f32_e32 v1, v1
	v_mul_f32_e32 v0, v4, v0
	v_cndmask_b32_e32 v0, 0, v0, vcc
	ds_write_b32 v70, v0
	v_sub_f32_e32 v0, v2, v85
	v_mul_f32_e32 v5, v5, v67
	v_exp_f32_e32 v0, v0
	v_mul_f32_e32 v1, v5, v1
	v_cmp_ge_i32_e32 vcc, v93, v126
	v_mul_f32_e32 v2, v6, v68
	v_mul_f32_e32 v0, v2, v0
	v_cndmask_b32_e32 v1, 0, v1, vcc
	ds_write_b32 v72, v1
	v_add_u32_e32 v1, 10, v129
	v_cmp_gt_i32_e32 vcc, v1, v126
	v_add_u32_e32 v68, 16, v129
	s_nop 0
	v_cndmask_b32_e32 v2, 0, v0, vcc
	v_add_u32_e32 v0, s14, v1
	v_mad_u64_u32 v[0:1], s[8:9], v0, s67, v[82:83]
	v_sub_f32_e32 v1, v3, v85
	v_exp_f32_e32 v1, v1
	ds_write_b32 v0, v2
	v_add_u32_e32 v0, 11, v129
	v_mul_f32_e32 v2, v7, v69
	v_mul_f32_e32 v1, v2, v1
	v_cmp_gt_i32_e32 vcc, v0, v126
	v_add_u32_e32 v0, s14, v0
	s_nop 0
	v_cndmask_b32_e32 v2, 0, v1, vcc
	v_mad_u64_u32 v[0:1], s[8:9], v0, s67, v[82:83]
	ds_write_b32 v0, v2
	ds_read_b128 v[0:3], v96 offset:64
	ds_read_b128 v[4:7], v96 offset:320
	v_cmp_gt_u32_e32 vcc, 16, v126
	v_cmp_gt_i32_e64 s[8:9], v68, v126
	s_waitcnt lgkmcnt(1)
	v_sub_f32_e32 v0, v0, v85
	v_exp_f32_e32 v0, v0
	s_waitcnt lgkmcnt(0)
	v_mul_f32_e32 v4, v8, v4
	v_cndmask_b32_e32 v65, v65, v126, vcc
	v_sub_f32_e32 v1, v1, v85
	v_mul_f32_e32 v0, v4, v0
	v_add_u32_e32 v4, s14, v68
	v_cndmask_b32_e64 v0, 0, v0, s[8:9]
	v_mad_u64_u32 v[66:67], s[8:9], v4, s67, v[82:83]
	v_mul_lo_u32 v4, v68, s75
	v_lshlrev_b32_e32 v8, 1, v65
	v_exp_f32_e32 v1, v1
	v_add3_u32 v65, s48, v4, v8
	ds_write_b32 v66, v0
	v_cvt_pk_bf16_f32 v0, v0, s0
	v_add_u32_e32 v4, 0xfffffb00, v65
	ds_write_b16 v4, v0
	v_mul_f32_e32 v0, v9, v5
	v_mul_f32_e32 v0, v0, v1
	v_sub_f32_e32 v1, v2, v85
	v_cmp_ge_i32_e64 s[8:9], v68, v126
	v_exp_f32_e32 v1, v1
	v_add3_u32 v64, v141, s48, v8
	v_cndmask_b32_e64 v0, 0, v0, s[8:9]
	ds_write_b32 v84, v0 offset:2448
	v_cvt_pk_bf16_f32 v0, v0, s0
	ds_write_b16 v64, v0 offset:80
	v_add_u32_e32 v0, 18, v129
	v_mul_f32_e32 v2, v10, v6
	v_mul_f32_e32 v1, v2, v1
	v_cmp_gt_i32_e64 s[8:9], v0, v126
	v_add_u32_e32 v0, s14, v0
	v_add_u32_e32 v10, 24, v129
	v_cndmask_b32_e64 v2, 0, v1, s[8:9]
	v_mad_u64_u32 v[0:1], s[8:9], v0, s67, v[82:83]
	v_sub_f32_e32 v1, v3, v85
	v_exp_f32_e32 v1, v1
	ds_write_b32 v0, v2
	v_cvt_pk_bf16_f32 v0, v2, s0
	ds_write_b16 v64, v0 offset:160
	v_add_u32_e32 v0, 19, v129
	v_mul_f32_e32 v2, v11, v7
	v_mul_f32_e32 v1, v2, v1
	v_cmp_gt_i32_e64 s[8:9], v0, v126
	v_add_u32_e32 v0, s14, v0
	s_nop 0
	v_cndmask_b32_e64 v2, 0, v1, s[8:9]
	v_mad_u64_u32 v[0:1], s[8:9], v0, s67, v[82:83]
	ds_write_b32 v0, v2
	v_cvt_pk_bf16_f32 v0, v2, s0
	ds_write_b16 v64, v0 offset:240
	ds_read_b128 v[0:3], v96 offset:96
	ds_read_b128 v[4:7], v96 offset:352
	v_cmp_gt_i32_e64 s[8:9], v10, v126
	s_waitcnt lgkmcnt(1)
; DI bf16_t f2bf(float a) { return (bf16_t)(pk2(a, 0.f) & 0xffffu); }
; DI float fnma_(float a, float x, float acc) { asm("v_fma_f32 %0, -%1, %2, %0" : "+v"(acc) : "v"(a), "v"(x)); return acc; }
; template <bool CONS>
; DI void dn_chain_role(const Params& p, unsigned char* smem, int dir, int b, int h) {
;     ...
;                 for (int g4 = 0; g4 < 4; ++g4) { const int il0 = 8 * g4 + 4 * hh; const f32x4 gi = *(const f32x4*)(sG + 32 * blk + il0), bi = *(const f32x4*)(sBeta + 32 * blk + il0);
; #pragma unroll
;                     for (int t = 0; t < 4; ++t) { const int il = il0 + t; const float v = il > r ? acc[4 * g4 + t] * bi[t] * __builtin_amdgcn_exp2f(gi[t] - Gj) : 0.f;
;                         sAd[(blk * 32 + il) * 36 + r] = v;
;                         if (g4 >= 2) sM1b[(il - 16) * 40 + m1col] = f2bf(v); } }
;             }
;             asm volatile("s_waitcnt lgkmcnt(0)" ::: "memory");
;             __builtin_amdgcn_wave_barrier();
;             const int sub = (lane >> 4) & 1, c = lane & 15;
;             const float* Ab = sAd + (blk * 32 + 16 * sub) * 36 + 16 * sub;
;             f32x4 ar[16][4];
; #pragma unroll
;             for (int i = 1; i < 16; ++i)
; #pragma unroll
;                 for (int q = 0; q < (i + 3) / 4; ++q) ar[i][q] = *(const f32x4*)(Ab + i * 36 + 4 * q);
;             float x[16];
; #pragma unroll
;             for (int i = 0; i < 16; ++i) {
;                 float acc = (i == c) ? 1.f : 0.f;
; #pragma unroll
;                 for (int j = 0; j < i; ++j) acc = fnma_(ar[i][j >> 2][j & 3], x[j], acc);
;                 x[i] = acc;
;             }
	v_sub_f32_e32 v0, v0, v85
	v_exp_f32_e32 v0, v0
	s_waitcnt lgkmcnt(0)
	v_mul_f32_e32 v4, v12, v4
	v_sub_f32_e32 v1, v1, v85
	v_exp_f32_e32 v1, v1
	v_mul_f32_e32 v0, v4, v0
	v_add_u32_e32 v4, s14, v10
	v_cndmask_b32_e64 v0, 0, v0, s[8:9]
	v_mad_u64_u32 v[8:9], s[8:9], v4, s67, v[82:83]
	ds_write_b32 v8, v0
	v_cvt_pk_bf16_f32 v0, v0, s0
	v_add_u32_e32 v4, 0xfffffd80, v65
	ds_write_b16 v4, v0
	v_mul_f32_e32 v0, v13, v5
	v_mul_f32_e32 v0, v0, v1
	v_sub_f32_e32 v1, v2, v85
	v_cmp_ge_i32_e64 s[8:9], v10, v126
	v_exp_f32_e32 v1, v1
	v_mul_f32_e32 v2, v14, v6
	v_cndmask_b32_e64 v0, 0, v0, s[8:9]
	ds_write_b32 v84, v0 offset:3600
	v_cvt_pk_bf16_f32 v0, v0, s0
	ds_write_b16 v64, v0 offset:720
	v_add_u32_e32 v0, 26, v129
	v_mul_f32_e32 v1, v2, v1
	v_cmp_gt_i32_e64 s[8:9], v0, v126
	v_add_u32_e32 v0, s14, v0
	s_nop 0
	v_cndmask_b32_e64 v2, 0, v1, s[8:9]
	v_mad_u64_u32 v[0:1], s[8:9], v0, s67, v[82:83]
	v_sub_f32_e32 v1, v3, v85
	v_exp_f32_e32 v1, v1
	ds_write_b32 v0, v2
	v_cvt_pk_bf16_f32 v0, v2, s0
	ds_write_b16 v64, v0 offset:800
	v_add_u32_e32 v0, 27, v129
	v_mul_f32_e32 v2, v15, v7
	v_mul_f32_e32 v1, v2, v1
	v_cmp_gt_i32_e64 s[8:9], v0, v126
	v_add_u32_e32 v0, s14, v0
	s_nop 0
	v_cndmask_b32_e64 v2, 0, v1, s[8:9]
	v_mad_u64_u32 v[0:1], s[8:9], v0, s67, v[82:83]
	ds_write_b32 v0, v2
	v_cvt_pk_bf16_f32 v0, v2, s0
	ds_write_b16 v64, v0 offset:880
	v_lshl_or_b32 v0, v178, 4, s14
	v_mul_u32_u24_e32 v0, 0x90, v0
	v_lshlrev_b32_e32 v1, 6, v178
	v_add3_u32 v0, s74, v0, v1
	s_waitcnt lgkmcnt(0)
	ds_read_b128 v[2:5], v0 offset:144
	s_waitcnt lgkmcnt(0)
	ds_read_b128 v[4:7], v0 offset:288
	s_waitcnt lgkmcnt(0)
	ds_read_b128 v[6:9], v0 offset:432
	ds_read_b128 v[10:13], v0 offset:576
	ds_read_b128 v[142:145], v0 offset:720
	ds_read_b128 v[146:149], v0 offset:736
	s_waitcnt lgkmcnt(0)
	ds_read_b128 v[148:151], v0 offset:864
	ds_read_b128 v[152:155], v0 offset:880
	s_waitcnt lgkmcnt(0)
	ds_read_b128 v[154:157], v0 offset:1008
	ds_read_b128 v[158:161], v0 offset:1024
	ds_read_b128 v[162:165], v0 offset:1152
	ds_read_b128 v[166:169], v0 offset:1168
	ds_read_b128 v[170:173], v0 offset:1296
	ds_read_b128 v[174:177], v0 offset:1312
	ds_read_b128 v[182:185], v0 offset:1328
	v_and_b32_e32 v1, 15, v138
	s_waitcnt lgkmcnt(0)
	ds_read_b128 v[184:187], v0 offset:1440
	ds_read_b128 v[188:191], v0 offset:1456
	ds_read_b128 v[192:195], v0 offset:1472
	v_cmp_eq_u32_e64 s[8:9], 0, v1
	s_waitcnt lgkmcnt(0)
	ds_read_b128 v[194:197], v0 offset:1584
	ds_read_b128 v[198:201], v0 offset:1600
	ds_read_b128 v[202:205], v0 offset:1616
	ds_read_b128 v[120:123], v0 offset:1728
	ds_read_b128 v[116:119], v0 offset:1744
	ds_read_b128 v[112:115], v0 offset:1760
	ds_read_b128 v[108:111], v0 offset:1872
	ds_read_b128 v[104:107], v0 offset:1888
	ds_read_b128 v[100:103], v0 offset:1904
	ds_read_b128 v[96:99], v0 offset:1920
	ds_read_b128 v[92:95], v0 offset:2016
	ds_read_b128 v[88:91], v0 offset:2032
	ds_read_b128 v[84:87], v0 offset:2048
	ds_read_b128 v[80:83], v0 offset:2064
	ds_read_b128 v[76:79], v0 offset:2160
	ds_read_b128 v[72:75], v0 offset:2176
	ds_read_b128 v[68:71], v0 offset:2192
	ds_read_b128 v[64:67], v0 offset:2208
	v_cndmask_b32_e64 v0, 0, 1.0, s[8:9]
	v_cmp_eq_u32_e64 s[8:9], 1, v1
	s_nop 1
	v_cndmask_b32_e64 v3, 0, 1.0, s[8:9]
	v_cmp_eq_u32_e64 s[8:9], 2, v1
	v_fma_f32 v3, -v2, v0, v3
	s_nop 1
	v_cndmask_b32_e64 v2, 0, 1.0, s[8:9]
	v_fma_f32 v2, -v4, v0, v2
	v_cmp_eq_u32_e64 s[8:9], 3, v1
	v_fma_f32 v2, -v5, v3, v2
	s_nop 1
	v_cndmask_b32_e64 v5, 0, 1.0, s[8:9]
	v_cmp_eq_u32_e64 s[8:9], 4, v1
	v_fma_f32 v5, -v6, v0, v5
	s_nop 0
	v_fma_f32 v5, -v7, v3, v5
	s_nop 0
	v_cndmask_b32_e64 v4, 0, 1.0, s[8:9]
	v_cmp_eq_u32_e64 s[8:9], 5, v1
	v_fma_f32 v5, -v8, v2, v5
	v_fma_f32 v4, -v10, v0, v4
	s_nop 0
	v_fma_f32 v4, -v11, v3, v4
	s_nop 0
	v_cndmask_b32_e64 v7, 0, 1.0, s[8:9]
	v_cmp_eq_u32_e64 s[8:9], 6, v1
	v_fma_f32 v4, -v12, v2, v4
	v_fma_f32 v7, -v142, v0, v7
	s_nop 0
	v_fma_f32 v4, -v13, v5, v4
	v_fma_f32 v7, -v143, v3, v7
	s_nop 0
	v_cndmask_b32_e64 v6, 0, 1.0, s[8:9]
	v_cmp_eq_u32_e64 s[8:9], 7, v1
	v_fma_f32 v6, -v148, v0, v6
	v_fma_f32 v7, -v144, v2, v7
	s_nop 0
	v_fma_f32 v6, -v149, v3, v6
	v_fma_f32 v7, -v145, v5, v7
	s_nop 0
	v_cndmask_b32_e64 v9, 0, 1.0, s[8:9]
	v_cmp_eq_u32_e64 s[8:9], 8, v1
	v_fma_f32 v9, -v154, v0, v9
	v_fma_f32 v6, -v150, v2, v6
	v_fma_f32 v7, -v146, v4, v7
	s_nop 0
	v_fma_f32 v9, -v155, v3, v9
	s_nop 0
	v_cndmask_b32_e64 v8, 0, 1.0, s[8:9]
	v_cmp_eq_u32_e64 s[8:9], 9, v1
	v_fma_f32 v8, -v162, v0, v8
	v_fma_f32 v9, -v156, v2, v9
	v_fma_f32 v6, -v151, v5, v6
	s_nop 0
	v_fma_f32 v8, -v163, v3, v8
	s_nop 0
	v_cndmask_b32_e64 v11, 0, 1.0, s[8:9]
	v_cmp_eq_u32_e64 s[8:9], 10, v1
	v_fma_f32 v11, -v170, v0, v11
	v_fma_f32 v8, -v164, v2, v8
	v_fma_f32 v9, -v157, v5, v9
	v_fma_f32 v6, -v152, v4, v6
	s_nop 0
	v_fma_f32 v11, -v171, v3, v11
	s_nop 0
	v_cndmask_b32_e64 v10, 0, 1.0, s[8:9]
	v_cmp_eq_u32_e64 s[8:9], 11, v1
	v_fma_f32 v10, -v184, v0, v10
	v_fma_f32 v11, -v172, v2, v11
	v_fma_f32 v8, -v165, v5, v8
	v_fma_f32 v9, -v158, v4, v9
	v_fma_f32 v6, -v153, v7, v6
	s_nop 1
	v_cndmask_b32_e64 v13, 0, 1.0, s[8:9]
	v_cmp_eq_u32_e64 s[8:9], 12, v1
	s_waitcnt lgkmcnt(14)
; DI unsigned pk2(float a, float b) { f32x2 v = {a, b}; bf16x2_t r = __builtin_convertvector(v, bf16x2_t); return __builtin_bit_cast(unsigned, r); }
; DI bf16_t f2bf(float a) { return (bf16_t)(pk2(a, 0.f) & 0xffffu); }
; DI float fnma_(float a, float x, float acc) { asm("v_fma_f32 %0, -%1, %2, %0" : "+v"(acc) : "v"(a), "v"(x)); return acc; }
; template <bool CONS>
; DI void dn_chain_role(const Params& p, unsigned char* smem, int dir, int b, int h) {
;     ...
;             for (int i = 0; i < 16; ++i) {
;                 float acc = (i == c) ? 1.f : 0.f;
; #pragma unroll
;                 for (int j = 0; j < i; ++j) acc = fnma_(ar[i][j >> 2][j & 3], x[j], acc);
;                 x[i] = acc;
;             }
;             { bf16_t* Tq = Tb + (16 * sub) * 40 + 16 * sub + c;
; #pragma unroll
;               for (int i = 0; i < 16; ++i) Tq[i * 40] = f2bf(x[i]); }
;             if (sub == 0) {
;                 u32x4 xl, xh;
;                 xl.x = pk2(x[0], x[1]); xl.y = pk2(x[2], x[3]); xl.z = pk2(x[4], x[5]); xl.w = pk2(x[6], x[7]);
;                 xh.x = pk2(x[8], x[9]); xh.y = pk2(x[10], x[11]); xh.z = pk2(x[12], x[13]); xh.w = pk2(x[14], x[15]);
;                 *(u32x4*)(sM2Tb + c * 40) = xl; *(u32x4*)(sM2Tb + c * 40 + 8) = xh;
;             } else {
; #pragma unroll
;                 for (int i = 0; i < 16; ++i) sM3b[i * 40 + c] = f2bf(x[i]);
	v_fma_f32 v13, -v194, v0, v13
	v_fma_f32 v10, -v185, v3, v10
	v_fma_f32 v11, -v173, v5, v11
	v_fma_f32 v8, -v166, v4, v8
	v_fma_f32 v9, -v159, v7, v9
	s_nop 0
	v_cndmask_b32_e64 v12, 0, 1.0, s[8:9]
	v_cmp_eq_u32_e64 s[8:9], 13, v1
	v_fma_f32 v12, -v120, v0, v12
	v_fma_f32 v13, -v195, v3, v13
	v_fma_f32 v10, -v186, v2, v10
	v_fma_f32 v11, -v174, v4, v11
	v_fma_f32 v8, -v167, v7, v8
	s_nop 1
	v_cndmask_b32_e64 v15, 0, 1.0, s[8:9]
	v_cmp_eq_u32_e64 s[8:9], 14, v1
	s_waitcnt lgkmcnt(11)
	v_fma_f32 v15, -v108, v0, v15
	v_fma_f32 v12, -v121, v3, v12
	v_fma_f32 v13, -v196, v2, v13
	v_fma_f32 v10, -v187, v5, v10
	v_fma_f32 v11, -v175, v7, v11
	s_nop 0
	v_cndmask_b32_e64 v14, 0, 1.0, s[8:9]
	v_cmp_eq_u32_e64 s[8:9], 15, v1
	s_waitcnt lgkmcnt(7)
	v_fma_f32 v14, -v92, v0, v14
	v_fma_f32 v15, -v109, v3, v15
	v_fma_f32 v12, -v122, v2, v12
	v_fma_f32 v13, -v197, v5, v13
	v_fma_f32 v10, -v188, v4, v10
	s_waitcnt lgkmcnt(0)
	v_cndmask_b32_e64 v67, 0, 1.0, s[8:9]
	v_fma_f32 v67, -v76, v0, v67
	v_fma_f32 v14, -v93, v3, v14
	v_fma_f32 v15, -v110, v2, v15
	v_fma_f32 v12, -v123, v5, v12
	v_fma_f32 v13, -v198, v4, v13
	v_fma_f32 v10, -v189, v7, v10
	s_nop 0
	v_fma_f32 v67, -v77, v3, v67
	v_fma_f32 v14, -v94, v2, v14
	v_fma_f32 v15, -v111, v5, v15
	v_fma_f32 v12, -v116, v4, v12
	v_fma_f32 v13, -v199, v7, v13
	v_fma_f32 v9, -v160, v6, v9
	s_nop 0
	v_fma_f32 v67, -v78, v2, v67
	v_fma_f32 v14, -v95, v5, v14
	v_fma_f32 v15, -v104, v4, v15
	v_fma_f32 v12, -v117, v7, v12
	v_fma_f32 v8, -v168, v6, v8
	v_fma_f32 v11, -v176, v6, v11
	s_nop 0
	v_fma_f32 v67, -v79, v5, v67
	v_fma_f32 v14, -v88, v4, v14
	v_fma_f32 v15, -v105, v7, v15
	v_fma_f32 v10, -v190, v6, v10
	v_fma_f32 v13, -v200, v6, v13
	v_fma_f32 v12, -v118, v6, v12
	s_nop 0
	v_fma_f32 v67, -v72, v4, v67
	v_fma_f32 v14, -v89, v7, v14
	v_fma_f32 v15, -v106, v6, v15
	v_fma_f32 v8, -v169, v9, v8
	v_fma_f32 v11, -v177, v9, v11
	v_fma_f32 v10, -v191, v9, v10
	s_nop 0
	v_fma_f32 v67, -v73, v7, v67
	v_fma_f32 v14, -v90, v6, v14
	v_fma_f32 v13, -v201, v9, v13
	v_fma_f32 v12, -v119, v9, v12
	v_fma_f32 v15, -v107, v9, v15
	v_fma_f32 v11, -v182, v8, v11
	s_nop 0
	v_fma_f32 v67, -v74, v6, v67
	v_fma_f32 v14, -v91, v9, v14
	v_fma_f32 v10, -v192, v8, v10
	v_fma_f32 v13, -v202, v8, v13
	v_fma_f32 v12, -v112, v8, v12
	v_fma_f32 v15, -v100, v8, v15
	s_nop 0
	v_fma_f32 v67, -v75, v9, v67
	v_fma_f32 v14, -v84, v8, v14
	v_fma_f32 v10, -v193, v11, v10
	v_fma_f32 v13, -v203, v11, v13
	v_fma_f32 v12, -v113, v11, v12
	v_fma_f32 v15, -v101, v11, v15
	s_nop 0
	v_fma_f32 v67, -v68, v8, v67
	v_fma_f32 v14, -v85, v11, v14
	v_cvt_pk_bf16_f32 v68, v5, s0
	v_fma_f32 v67, -v69, v11, v67
	v_fma_f32 v13, -v204, v10, v13
	v_fma_f32 v12, -v114, v10, v12
	v_fma_f32 v15, -v102, v10, v15
	v_fma_f32 v14, -v86, v10, v14
	v_cvt_pk_bf16_f32 v69, v4, s0
	v_fma_f32 v67, -v70, v10, v67
	v_fma_f32 v12, -v115, v13, v12
	v_fma_f32 v15, -v103, v13, v15
	v_fma_f32 v14, -v87, v13, v14
	v_cvt_pk_bf16_f32 v70, v7, s0
	v_fma_f32 v67, -v71, v13, v67
	v_fma_f32 v15, -v96, v12, v15
	v_fma_f32 v14, -v80, v12, v14
	v_cvt_pk_bf16_f32 v71, v6, s0
	v_fma_f32 v67, -v64, v12, v67
	v_mov_b32_e32 v64, s44
	v_fma_f32 v67, -v65, v15, v67
	v_fma_f32 v14, -v81, v15, v14
	v_mad_u32_u24 v64, v178, s77, v64
	v_fma_f32 v67, -v66, v14, v67
	v_lshlrev_b32_e32 v65, 5, v178
	v_lshlrev_b32_e32 v66, 1, v1
	v_add3_u32 v81, v64, v65, v66
	v_cvt_pk_bf16_f32 v64, v0, s0
	v_cvt_pk_bf16_f32 v65, v3, s0
	v_cvt_pk_bf16_f32 v66, v2, s0
	v_cvt_pk_bf16_f32 v72, v9, s0
	v_cvt_pk_bf16_f32 v73, v8, s0
	v_cvt_pk_bf16_f32 v74, v11, s0
	v_cvt_pk_bf16_f32 v75, v10, s0
	v_cvt_pk_bf16_f32 v76, v13, s0
	v_cvt_pk_bf16_f32 v77, v12, s0
	v_cvt_pk_bf16_f32 v78, v15, s0
	v_cvt_pk_bf16_f32 v79, v14, s0
	v_cvt_pk_bf16_f32 v80, v67, s0
	ds_write_b16 v81, v64
	ds_write_b16 v81, v65 offset:80
	ds_write_b16 v81, v66 offset:160
	ds_write_b16 v81, v68 offset:240
	ds_write_b16 v81, v69 offset:320
	ds_write_b16 v81, v70 offset:400
	ds_write_b16 v81, v71 offset:480
	ds_write_b16 v81, v72 offset:560
	ds_write_b16 v81, v73 offset:640
	ds_write_b16 v81, v74 offset:720
	ds_write_b16 v81, v75 offset:800
	ds_write_b16 v81, v76 offset:880
	ds_write_b16 v81, v77 offset:960
	ds_write_b16 v81, v78 offset:1040
	ds_write_b16 v81, v79 offset:1120
	ds_write_b16 v81, v80 offset:1200
	v_and_b32_e32 v81, 16, v138
	v_cmp_ne_u32_e64 s[8:9], 0, v81
	s_and_saveexec_b64 s[22:23], s[8:9]
	s_xor_b64 s[8:9], exec, s[22:23]
	s_cbranch_execz .LBB0_548
	v_lshl_add_u32 v1, v1, 1, s50
	ds_write_b16 v1, v64
	ds_write_b16 v1, v65 offset:80
	ds_write_b16 v1, v66 offset:160
	ds_write_b16 v1, v68 offset:240
	ds_write_b16 v1, v69 offset:320
	ds_write_b16 v1, v70 offset:400
	ds_write_b16 v1, v71 offset:480
	ds_write_b16 v1, v72 offset:560
	ds_write_b16 v1, v73 offset:640
	ds_write_b16 v1, v74 offset:720
	ds_write_b16 v1, v75 offset:800
	ds_write_b16 v1, v76 offset:880
	ds_write_b16 v1, v77 offset:960
	ds_write_b16 v1, v78 offset:1040
	ds_write_b16 v1, v79 offset:1120
	ds_write_b16 v1, v80 offset:1200
